# v118 + weight-conversion item loop software pipelined (load wait moved from the top of the body to the register hand-over at the bottom, vmcnt(8))
# baseline (speedup 1.0000x reference)
.LBB0_76:
	v_and_b32_e32 v164, 63, v165
	s_andn2_b64 vcc, exec, s[44:45]
	s_lshl_b32 s44, s88, 3
	s_lshr_b32 s44, s44, s101
	s_cbranch_vccnz .LBB0_154
	s_sub_i32 s44, 0, s44
	v_lshlrev_b32_e32 v18, 3, v165
	v_lshrrev_b32_e32 v186, 3, v164
	v_and_b32_e32 v34, 56, v18
	s_mulk_i32 s0, 0x4200
	v_mul_u32_u24_e32 v18, 0x104, v34
	v_mov_b32_e32 v19, 0
	s_add_i32 s0, s0, 0
	v_lshlrev_b32_e32 v20, 2, v186
	v_mul_u32_u24_e32 v35, 0x104, v1
	v_lshl_add_u32 v100, v170, 2, s0
	v_add3_u32 v194, s0, v18, v20
	v_mov_b32_e32 v20, v19
	v_mov_b32_e32 v21, v19
	v_mov_b32_e32 v22, v19
	v_mov_b32_e32 v23, v19
	v_mov_b32_e32 v24, v19
	v_mov_b32_e32 v25, v19
	v_mov_b32_e32 v26, v19
	v_mov_b32_e32 v27, v19
	v_mov_b32_e32 v28, v19
	v_mov_b32_e32 v29, v19
	v_mov_b32_e32 v30, v19
	v_mov_b32_e32 v31, v19
	v_mov_b32_e32 v32, v19
	v_mov_b32_e32 v33, v19
	v_writelane_b32 v228, s94, 16
	s_add_i32 s0, s44, s24
	v_mov_b32_e32 v18, v19
	v_add_u32_e32 v195, v100, v35
	v_lshlrev_b32_e32 v166, 1, v34
	v_mov_b64_e32 v[34:35], v[32:33]
	v_writelane_b32 v228, s95, 17
	v_or_b32_e32 v187, 8, v186
	v_or_b32_e32 v188, 16, v186
	v_or_b32_e32 v189, 24, v186
	v_or_b32_e32 v190, 32, v186
	v_or_b32_e32 v191, 40, v186
	v_or_b32_e32 v192, 48, v186
	v_or_b32_e32 v193, 56, v186
	s_lshl_b32 s25, s0, 6
	s_lshl_b32 s33, s44, 6
	s_lshl_b32 s45, s0, 1
	s_lshl_b32 s88, s44, 1
	s_lshl_b32 s89, s0, 3
	s_lshl_b32 s92, s44, 3
	s_lshl_b32 s93, s0, 2
	s_lshl_b32 s94, s44, 2
	s_mov_b32 s97, 0
	s_mov_b64 s[52:53], 0
	s_mov_b32 s95, 1.0
	s_mov_b32 s96, s24
	v_mov_b64_e32 v[32:33], v[30:31]
	v_mov_b64_e32 v[30:31], v[28:29]
	v_mov_b64_e32 v[28:29], v[26:27]
	v_mov_b64_e32 v[26:27], v[24:25]
	v_mov_b64_e32 v[24:25], v[22:23]
	v_mov_b64_e32 v[22:23], v[20:21]
	v_mov_b64_e32 v[20:21], v[18:19]
	s_mov_b32 s1, 0
	s_mov_b32 s0, 0
	s_waitcnt vmcnt(0)
	s_branch .LBB0_80
.LBB0_78:
	s_nop 0
	v_mov_b32_e32 v35, 1.0
.LBB0_79:
	s_nop 0
	v_pk_mul_f32 v[42:43], v[42:43], v[2:3] op_sel_hi:[1,0]
	v_pk_mul_f32 v[40:41], v[40:41], v[2:3] op_sel_hi:[1,0]
	v_pk_mul_f32 v[38:39], v[38:39], v[2:3] op_sel:[0,1]
	v_pk_mul_f32 v[2:3], v[36:37], v[2:3] op_sel:[0,1]
	v_add_u32_e32 v18, 0x410, v195
	ds_write2_b32 v195, v40, v41 offset1:1
	ds_write2_b32 v195, v42, v43 offset0:2 offset1:3
	ds_write2_b32 v18, v2, v3 offset1:1
	v_add_u32_e32 v2, 0x418, v195
	ds_write2_b32 v2, v38, v39 offset1:1
	v_pk_mul_f32 v[2:3], v[54:55], v[4:5] op_sel_hi:[1,0]
	v_pk_mul_f32 v[36:37], v[52:53], v[4:5] op_sel_hi:[1,0]
	v_add_u32_e32 v4, 0x820, v195
	ds_write2_b32 v4, v36, v37 offset1:1
	v_add_u32_e32 v4, 0x828, v195
	ds_write2_b32 v4, v2, v3 offset1:1
	v_mov_b32_e32 v2, v5
	v_pk_mul_f32 v[4:5], v[46:47], v[2:3] op_sel_hi:[1,0]
	v_pk_mul_f32 v[2:3], v[44:45], v[2:3] op_sel_hi:[1,0]
	v_add_u32_e32 v18, 0xc30, v195
	ds_write2_b32 v18, v2, v3 offset1:1
	v_add_u32_e32 v2, 0xc38, v195
	ds_write2_b32 v2, v4, v5 offset1:1
	v_pk_mul_f32 v[2:3], v[62:63], v[6:7] op_sel_hi:[1,0]
	v_pk_mul_f32 v[4:5], v[60:61], v[6:7] op_sel_hi:[1,0]
	v_add_u32_e32 v6, 0x1040, v195
	ds_write2_b32 v6, v4, v5 offset1:1
	v_add_u32_e32 v4, 0x1048, v195
	ds_write2_b32 v4, v2, v3 offset1:1
	v_mov_b32_e32 v2, v7
	v_pk_mul_f32 v[4:5], v[50:51], v[2:3] op_sel_hi:[1,0]
	v_pk_mul_f32 v[2:3], v[48:49], v[2:3] op_sel_hi:[1,0]
	v_add_u32_e32 v6, 0x1450, v195
	ds_write2_b32 v6, v2, v3 offset1:1
	v_add_u32_e32 v2, 0x1458, v195
	ds_write2_b32 v2, v4, v5 offset1:1
	v_pk_mul_f32 v[4:5], v[68:69], v[8:9] op_sel_hi:[1,0]
	v_add_u32_e32 v6, 0x1860, v195
	v_pk_mul_f32 v[2:3], v[70:71], v[8:9] op_sel_hi:[1,0]
	ds_write2_b32 v6, v4, v5 offset1:1
	v_add_u32_e32 v4, 0x1868, v195
	ds_write2_b32 v4, v2, v3 offset1:1
	v_mov_b32_e32 v2, v9
	v_pk_mul_f32 v[4:5], v[58:59], v[2:3] op_sel_hi:[1,0]
	v_pk_mul_f32 v[2:3], v[56:57], v[2:3] op_sel_hi:[1,0]
	v_add_u32_e32 v6, 0x1c70, v195
	ds_write2_b32 v6, v2, v3 offset1:1
	v_add_u32_e32 v2, 0x1c78, v195
	ds_write2_b32 v2, v4, v5 offset1:1
	v_pk_mul_f32 v[4:5], v[76:77], v[10:11] op_sel_hi:[1,0]
	v_add_u32_e32 v6, 0x2080, v195
	v_pk_mul_f32 v[2:3], v[78:79], v[10:11] op_sel_hi:[1,0]
	ds_write2_b32 v6, v4, v5 offset1:1
	v_add_u32_e32 v4, 0x2088, v195
	ds_write2_b32 v4, v2, v3 offset1:1
	v_mov_b32_e32 v2, v11
	v_pk_mul_f32 v[4:5], v[66:67], v[2:3] op_sel_hi:[1,0]
	v_pk_mul_f32 v[2:3], v[64:65], v[2:3] op_sel_hi:[1,0]
	v_add_u32_e32 v6, 0x2490, v195
	ds_write2_b32 v6, v2, v3 offset1:1
	v_add_u32_e32 v2, 0x2498, v195
	ds_write2_b32 v2, v4, v5 offset1:1
	v_pk_mul_f32 v[4:5], v[84:85], v[12:13] op_sel_hi:[1,0]
	v_add_u32_e32 v6, 0x28a0, v195
	v_pk_mul_f32 v[2:3], v[86:87], v[12:13] op_sel_hi:[1,0]
	ds_write2_b32 v6, v4, v5 offset1:1
	v_add_u32_e32 v4, 0x28a8, v195
	ds_write2_b32 v4, v2, v3 offset1:1
	v_mov_b32_e32 v2, v13
	v_pk_mul_f32 v[4:5], v[74:75], v[2:3] op_sel_hi:[1,0]
	v_pk_mul_f32 v[2:3], v[72:73], v[2:3] op_sel_hi:[1,0]
	v_add_u32_e32 v6, 0x2cb0, v195
	ds_write2_b32 v6, v2, v3 offset1:1
	v_add_u32_e32 v2, 0x2cb8, v195
	ds_write2_b32 v2, v4, v5 offset1:1
	v_pk_mul_f32 v[4:5], v[92:93], v[14:15] op_sel_hi:[1,0]
	v_add_u32_e32 v6, 0x30c0, v195
	v_pk_mul_f32 v[2:3], v[94:95], v[14:15] op_sel_hi:[1,0]
	ds_write2_b32 v6, v4, v5 offset1:1
	v_add_u32_e32 v4, 0x30c8, v195
	ds_write2_b32 v4, v2, v3 offset1:1
	v_mov_b32_e32 v2, v15
	v_pk_mul_f32 v[4:5], v[82:83], v[2:3] op_sel_hi:[1,0]
	v_pk_mul_f32 v[2:3], v[80:81], v[2:3] op_sel_hi:[1,0]
	v_add_u32_e32 v6, 0x34d0, v195
	ds_write2_b32 v6, v2, v3 offset1:1
	v_add_u32_e32 v2, 0x34d8, v195
	ds_write2_b32 v2, v4, v5 offset1:1
	v_pk_mul_f32 v[4:5], v[96:97], v[16:17] op_sel_hi:[1,0]
	v_add_u32_e32 v6, 0x38e0, v195
	v_pk_mul_f32 v[2:3], v[98:99], v[16:17] op_sel_hi:[1,0]
	ds_write2_b32 v6, v4, v5 offset1:1
	v_add_u32_e32 v4, 0x38e8, v195
	ds_write2_b32 v4, v2, v3 offset1:1
	v_mov_b32_e32 v2, v17
	v_pk_mul_f32 v[4:5], v[90:91], v[2:3] op_sel_hi:[1,0]
	v_pk_mul_f32 v[2:3], v[88:89], v[2:3] op_sel_hi:[1,0]
	v_add_u32_e32 v6, 0x3cf0, v195
	ds_write2_b32 v6, v2, v3 offset1:1
	v_add_u32_e32 v2, 0x3cf8, v195
	ds_write2_b32 v2, v4, v5 offset1:1
	s_waitcnt lgkmcnt(0)
	ds_read2_b32 v[2:3], v194 offset1:65
	s_waitcnt lgkmcnt(0)
	v_cvt_pk_bf16_f32 v2, v2, v3
	ds_read2_b32 v[4:5], v194 offset0:130 offset1:195
	v_add_u32_e32 v10, 0x400, v194
	s_waitcnt lgkmcnt(0)
	v_cvt_pk_bf16_f32 v3, v4, v5
	ds_read2_b32 v[4:5], v10 offset0:4 offset1:69
	s_waitcnt lgkmcnt(0)
	v_cvt_pk_bf16_f32 v4, v4, v5
	ds_read2_b32 v[6:7], v10 offset0:134 offset1:199
	s_waitcnt lgkmcnt(0)
	v_cvt_pk_bf16_f32 v5, v6, v7
	v_add_u32_e32 v6, s3, v186
	v_ashrrev_i32_e32 v9, 31, v6
	v_mad_u64_u32 v[6:7], s[4:5], v6, s2, 0
	v_mov_b32_e32 v8, v7
	v_mad_u64_u32 v[8:9], s[4:5], v9, s2, v[8:9]
	v_mov_b32_e32 v7, v8
	s_ashr_i32 s49, s48, 31
	v_lshl_add_u64 v[6:7], v[6:7], 1, s[46:47]
	s_lshl_b64 s[4:5], s[48:49], 1
	v_lshl_add_u64 v[6:7], v[6:7], 0, s[4:5]
	v_mov_b32_e32 v167, v19
	v_lshl_add_u64 v[6:7], v[6:7], 0, v[166:167]
	ds_read2_b32 v[8:9], v194 offset0:8 offset1:73
	global_store_dwordx4 v[6:7], v[2:5], off
	s_nop 0
	s_nop 0
	s_waitcnt lgkmcnt(0)
	v_cvt_pk_bf16_f32 v2, v8, v9
	ds_read2_b32 v[4:5], v194 offset0:138 offset1:203
	s_waitcnt lgkmcnt(0)
	v_cvt_pk_bf16_f32 v3, v4, v5
	ds_read2_b32 v[4:5], v10 offset0:12 offset1:77
	s_waitcnt lgkmcnt(0)
	v_cvt_pk_bf16_f32 v4, v4, v5
	ds_read2_b32 v[6:7], v10 offset0:142 offset1:207
	s_waitcnt lgkmcnt(0)
	v_cvt_pk_bf16_f32 v5, v6, v7
	v_add_u32_e32 v6, s3, v187
	v_ashrrev_i32_e32 v9, 31, v6
	v_mad_u64_u32 v[6:7], s[48:49], v6, s2, 0
	v_mov_b32_e32 v8, v7
	v_mad_u64_u32 v[8:9], s[48:49], v9, s2, v[8:9]
	v_mov_b32_e32 v7, v8
	v_lshl_add_u64 v[6:7], v[6:7], 1, s[46:47]
	v_lshl_add_u64 v[6:7], v[6:7], 0, s[4:5]
	v_lshl_add_u64 v[6:7], v[6:7], 0, v[166:167]
	ds_read2_b32 v[8:9], v194 offset0:16 offset1:81
	global_store_dwordx4 v[6:7], v[2:5], off
	s_nop 0
	s_nop 0
	s_waitcnt lgkmcnt(0)
	v_cvt_pk_bf16_f32 v2, v8, v9
	ds_read2_b32 v[4:5], v194 offset0:146 offset1:211
	s_waitcnt lgkmcnt(0)
	v_cvt_pk_bf16_f32 v3, v4, v5
	ds_read2_b32 v[4:5], v10 offset0:20 offset1:85
	s_waitcnt lgkmcnt(0)
	v_cvt_pk_bf16_f32 v4, v4, v5
	ds_read2_b32 v[6:7], v10 offset0:150 offset1:215
	s_waitcnt lgkmcnt(0)
	v_cvt_pk_bf16_f32 v5, v6, v7
	v_add_u32_e32 v6, s3, v188
	v_ashrrev_i32_e32 v9, 31, v6
	v_mad_u64_u32 v[6:7], s[48:49], v6, s2, 0
	v_mov_b32_e32 v8, v7
	v_mad_u64_u32 v[8:9], s[48:49], v9, s2, v[8:9]
	v_mov_b32_e32 v7, v8
	v_lshl_add_u64 v[6:7], v[6:7], 1, s[46:47]
	v_lshl_add_u64 v[6:7], v[6:7], 0, s[4:5]
	v_lshl_add_u64 v[6:7], v[6:7], 0, v[166:167]
	ds_read2_b32 v[8:9], v194 offset0:24 offset1:89
	global_store_dwordx4 v[6:7], v[2:5], off
	s_nop 0
	s_nop 0
	s_waitcnt lgkmcnt(0)
	v_cvt_pk_bf16_f32 v2, v8, v9
	ds_read2_b32 v[4:5], v194 offset0:154 offset1:219
	s_waitcnt lgkmcnt(0)
	v_cvt_pk_bf16_f32 v3, v4, v5
	ds_read2_b32 v[4:5], v10 offset0:28 offset1:93
	s_waitcnt lgkmcnt(0)
	v_cvt_pk_bf16_f32 v4, v4, v5
	ds_read2_b32 v[6:7], v10 offset0:158 offset1:223
	s_waitcnt lgkmcnt(0)
	v_cvt_pk_bf16_f32 v5, v6, v7
	v_add_u32_e32 v6, s3, v189
	v_ashrrev_i32_e32 v9, 31, v6
	v_mad_u64_u32 v[6:7], s[48:49], v6, s2, 0
	v_mov_b32_e32 v8, v7
	v_mad_u64_u32 v[8:9], s[48:49], v9, s2, v[8:9]
	v_mov_b32_e32 v7, v8
	v_lshl_add_u64 v[6:7], v[6:7], 1, s[46:47]
	v_lshl_add_u64 v[6:7], v[6:7], 0, s[4:5]
	v_lshl_add_u64 v[6:7], v[6:7], 0, v[166:167]
	ds_read2_b32 v[8:9], v194 offset0:32 offset1:97
	global_store_dwordx4 v[6:7], v[2:5], off
	s_nop 0
	s_nop 0
	s_waitcnt lgkmcnt(0)
	v_cvt_pk_bf16_f32 v2, v8, v9
	ds_read2_b32 v[4:5], v194 offset0:162 offset1:227
	s_waitcnt lgkmcnt(0)
	v_cvt_pk_bf16_f32 v3, v4, v5
	ds_read2_b32 v[4:5], v10 offset0:36 offset1:101
	s_waitcnt lgkmcnt(0)
	v_cvt_pk_bf16_f32 v4, v4, v5
	ds_read2_b32 v[6:7], v10 offset0:166 offset1:231
	s_waitcnt lgkmcnt(0)
	v_cvt_pk_bf16_f32 v5, v6, v7
	v_add_u32_e32 v6, s3, v190
	v_ashrrev_i32_e32 v9, 31, v6
	v_mad_u64_u32 v[6:7], s[48:49], v6, s2, 0
	v_mov_b32_e32 v8, v7
	v_mad_u64_u32 v[8:9], s[48:49], v9, s2, v[8:9]
	v_mov_b32_e32 v7, v8
	v_lshl_add_u64 v[6:7], v[6:7], 1, s[46:47]
	v_lshl_add_u64 v[6:7], v[6:7], 0, s[4:5]
	v_lshl_add_u64 v[6:7], v[6:7], 0, v[166:167]
	ds_read2_b32 v[8:9], v194 offset0:40 offset1:105
	global_store_dwordx4 v[6:7], v[2:5], off
	s_nop 0
	s_nop 0
	s_waitcnt lgkmcnt(0)
	v_cvt_pk_bf16_f32 v2, v8, v9
	ds_read2_b32 v[4:5], v194 offset0:170 offset1:235
	s_waitcnt lgkmcnt(0)
	v_cvt_pk_bf16_f32 v3, v4, v5
	ds_read2_b32 v[4:5], v10 offset0:44 offset1:109
	s_waitcnt lgkmcnt(0)
	v_cvt_pk_bf16_f32 v4, v4, v5
	ds_read2_b32 v[6:7], v10 offset0:174 offset1:239
	s_waitcnt lgkmcnt(0)
	v_cvt_pk_bf16_f32 v5, v6, v7
	v_add_u32_e32 v6, s3, v191
	v_ashrrev_i32_e32 v9, 31, v6
	v_mad_u64_u32 v[6:7], s[48:49], v6, s2, 0
	v_mov_b32_e32 v8, v7
	v_mad_u64_u32 v[8:9], s[48:49], v9, s2, v[8:9]
	v_mov_b32_e32 v7, v8
	v_lshl_add_u64 v[6:7], v[6:7], 1, s[46:47]
	v_lshl_add_u64 v[6:7], v[6:7], 0, s[4:5]
	v_lshl_add_u64 v[6:7], v[6:7], 0, v[166:167]
	ds_read2_b32 v[8:9], v194 offset0:48 offset1:113
	global_store_dwordx4 v[6:7], v[2:5], off
	s_nop 0
	s_nop 0
	s_waitcnt lgkmcnt(0)
	v_cvt_pk_bf16_f32 v2, v8, v9
	ds_read2_b32 v[4:5], v194 offset0:178 offset1:243
	s_waitcnt lgkmcnt(0)
	v_cvt_pk_bf16_f32 v3, v4, v5
	ds_read2_b32 v[4:5], v10 offset0:52 offset1:117
	s_waitcnt lgkmcnt(0)
	v_cvt_pk_bf16_f32 v4, v4, v5
	ds_read2_b32 v[6:7], v10 offset0:182 offset1:247
	s_waitcnt lgkmcnt(0)
	v_cvt_pk_bf16_f32 v5, v6, v7
	v_add_u32_e32 v6, s3, v192
	v_ashrrev_i32_e32 v9, 31, v6
	v_mad_u64_u32 v[6:7], s[48:49], v6, s2, 0
	v_mov_b32_e32 v8, v7
	v_mad_u64_u32 v[8:9], s[48:49], v9, s2, v[8:9]
	v_mov_b32_e32 v7, v8
	v_lshl_add_u64 v[6:7], v[6:7], 1, s[46:47]
	v_lshl_add_u64 v[6:7], v[6:7], 0, s[4:5]
	v_lshl_add_u64 v[6:7], v[6:7], 0, v[166:167]
	ds_read2_b32 v[8:9], v194 offset0:56 offset1:121
	global_store_dwordx4 v[6:7], v[2:5], off
	s_nop 0
	s_nop 0
	s_waitcnt lgkmcnt(0)
	v_cvt_pk_bf16_f32 v2, v8, v9
	ds_read2_b32 v[4:5], v194 offset0:186 offset1:251
	s_waitcnt lgkmcnt(0)
	v_cvt_pk_bf16_f32 v3, v4, v5
	ds_read2_b32 v[4:5], v10 offset0:60 offset1:125
	s_waitcnt lgkmcnt(0)
	v_cvt_pk_bf16_f32 v4, v4, v5
	ds_read2_b32 v[6:7], v10 offset0:190 offset1:255
	s_waitcnt lgkmcnt(0)
	v_cvt_pk_bf16_f32 v5, v6, v7
	v_add_u32_e32 v6, s3, v193
	v_ashrrev_i32_e32 v9, 31, v6
	v_mad_u64_u32 v[6:7], s[48:49], v6, s2, 0
	v_mov_b32_e32 v8, v7
	v_mad_u64_u32 v[8:9], s[2:3], v9, s2, v[8:9]
	v_mov_b32_e32 v7, v8
	v_lshl_add_u64 v[6:7], v[6:7], 1, s[46:47]
	v_lshl_add_u64 v[6:7], v[6:7], 0, s[4:5]
	v_lshl_add_u64 v[6:7], v[6:7], 0, v[166:167]
	global_store_dwordx4 v[6:7], v[2:5], off
	s_waitcnt lgkmcnt(0)
	s_waitcnt vmcnt(8)
	v_mov_b64_e32 v[88:89], v[160:161]
	v_mov_b64_e32 v[96:97], v[156:157]
	v_mov_b64_e32 v[80:81], v[152:153]
	v_mov_b64_e32 v[92:93], v[148:149]
	v_mov_b64_e32 v[72:73], v[144:145]
	v_mov_b64_e32 v[84:85], v[140:141]
	v_mov_b64_e32 v[64:65], v[136:137]
	v_mov_b64_e32 v[76:77], v[132:133]
	v_mov_b64_e32 v[56:57], v[128:129]
	v_mov_b64_e32 v[68:69], v[124:125]
	v_mov_b64_e32 v[48:49], v[120:121]
	v_mov_b64_e32 v[60:61], v[116:117]
	v_mov_b64_e32 v[44:45], v[112:113]
	v_mov_b64_e32 v[52:53], v[108:109]
	v_mov_b64_e32 v[36:37], v[104:105]
	v_mov_b64_e32 v[40:41], v[100:101]
	v_mov_b64_e32 v[2:3], v[20:21]
	v_mov_b64_e32 v[90:91], v[162:163]
	v_mov_b64_e32 v[98:99], v[158:159]
	v_mov_b64_e32 v[82:83], v[154:155]
	v_mov_b64_e32 v[94:95], v[150:151]
	v_mov_b64_e32 v[74:75], v[146:147]
	v_mov_b64_e32 v[86:87], v[142:143]
	v_mov_b64_e32 v[66:67], v[138:139]
	v_mov_b64_e32 v[78:79], v[134:135]
	v_mov_b64_e32 v[58:59], v[130:131]
	v_mov_b64_e32 v[70:71], v[126:127]
	v_mov_b64_e32 v[50:51], v[122:123]
	v_mov_b64_e32 v[62:63], v[118:119]
	v_mov_b64_e32 v[46:47], v[114:115]
	v_mov_b64_e32 v[54:55], v[110:111]
	v_mov_b64_e32 v[38:39], v[106:107]
	v_mov_b64_e32 v[42:43], v[102:103]
	v_mov_b64_e32 v[4:5], v[22:23]
	v_mov_b64_e32 v[6:7], v[24:25]
	v_mov_b64_e32 v[8:9], v[26:27]
	v_mov_b64_e32 v[10:11], v[28:29]
	v_mov_b64_e32 v[12:13], v[30:31]
	v_mov_b64_e32 v[14:15], v[32:33]
	v_mov_b64_e32 v[16:17], v[34:35]
	s_add_i32 s25, s25, s33
	s_add_i32 s45, s45, s88
	s_add_i32 s89, s89, s92
	s_add_i32 s93, s93, s94
	s_andn2_b64 vcc, exec, s[50:51]
	s_mov_b32 s48, s97
	s_mov_b32 s3, s1
	s_mov_b32 s2, s0
	s_mov_b64 s[46:47], s[52:53]
	s_cbranch_vccz .LBB0_155

.LBB0_124:
	v_readlane_b32 s90, v228, 10
	v_readlane_b32 s91, v228, 11
	s_andn2_b64 vcc, exec, s[4:5]
	s_cbranch_vccnz .LBB0_126
	s_nop 0
	v_mov_b32_e32 v21, 1.0

.LBB0_129:
	v_readlane_b32 s56, v228, 8
	v_readlane_b32 s57, v228, 9
	s_andn2_b64 vcc, exec, s[54:55]
	s_cbranch_vccnz .LBB0_131
	s_nop 0
	v_mov_b32_e32 v23, 1.0

.LBB0_133:
	s_nop 0
	v_mov_b32_e32 v25, 1.0

.LBB0_136:
	s_nop 0
	v_mov_b32_e32 v27, 1.0

.LBB0_139:
	s_nop 0
	v_mov_b32_e32 v29, 1.0

.LBB0_142:
	s_nop 0
	v_mov_b32_e32 v31, 1.0

.LBB0_145:
	s_nop 0
	v_mov_b32_e32 v33, 1.0
